# S loop: per-list-entry 16-token selection masks precomputed once per tile (one readlane per step decides group activity; block id and bias masks only on the active path)
# speedup vs baseline: 1.0314x; 1.0016x over previous
.LBB0_2164:
	s_or_b64 exec, exec, s[20:21]
	v_add_u32_e32 v38, v34, v35
	v_bcnt_u32_b32 v37, v37, 0
	v_add_u32_e32 v38, v38, v36
	v_add_u32_e32 v150, v38, v37
	v_mul_f32_e32 v38, v133, v146
	v_cmp_eq_u32_e32 vcc, 0, v150
	v_pk_mul_f32 v[82:83], v[38:39], v[18:19] op_sel_hi:[0,1]
	v_add_u32_e32 v215, 0x9000, v214
	v_pk_mul_f32 v[84:85], v[38:39], v[20:21] op_sel_hi:[0,1]
	v_add_u32_e32 v216, 0x9008, v214
	v_pk_mul_f32 v[86:87], v[38:39], v[22:23] op_sel_hi:[0,1]
	v_add_u32_e32 v217, 0x9020, v214
	v_pk_mul_f32 v[88:89], v[38:39], v[24:25] op_sel_hi:[0,1]
	v_add_u32_e32 v218, 0x9028, v214
	v_pk_mul_f32 v[90:91], v[38:39], v[26:27] op_sel_hi:[0,1]
	v_add_u32_e32 v219, 0x9040, v214
	v_pk_mul_f32 v[92:93], v[38:39], v[28:29] op_sel_hi:[0,1]
	v_add_u32_e32 v220, 0x9048, v214
	v_pk_mul_f32 v[94:95], v[38:39], v[30:31] op_sel_hi:[0,1]
	v_add_u32_e32 v221, 0x9060, v214
	v_pk_mul_f32 v[96:97], v[38:39], v[32:33] op_sel_hi:[0,1]
	v_add_u32_e32 v222, 0x9068, v214
	v_pk_mul_f32 v[134:135], v[38:39], v[2:3] op_sel_hi:[0,1]
	v_add_u32_e32 v223, 0x9080, v214
	v_pk_mul_f32 v[136:137], v[38:39], v[4:5] op_sel_hi:[0,1]
	v_add_u32_e32 v224, 0x9088, v214
	v_pk_mul_f32 v[138:139], v[38:39], v[6:7] op_sel_hi:[0,1]
	v_add_u32_e32 v225, 0x90a0, v214
	v_pk_mul_f32 v[140:141], v[38:39], v[8:9] op_sel_hi:[0,1]
	v_add_u32_e32 v226, 0x90a8, v214
	v_pk_mul_f32 v[142:143], v[38:39], v[10:11] op_sel_hi:[0,1]
	v_add_u32_e32 v227, 0x90c0, v214
	v_pk_mul_f32 v[144:145], v[38:39], v[12:13] op_sel_hi:[0,1]
	v_add_u32_e32 v228, 0x90c8, v214
	v_pk_mul_f32 v[146:147], v[38:39], v[14:15] op_sel_hi:[0,1]
	v_add_u32_e32 v229, 0x90e0, v214
	v_pk_mul_f32 v[148:149], v[38:39], v[16:17] op_sel_hi:[0,1]
	v_add_u32_e32 v230, 0x90e8, v214
	s_and_b64 vcc, exec, vcc
	s_lshl_b32 s24, s71, 19
	s_waitcnt lgkmcnt(0)
	s_barrier
	ds_write2_b32 v215, v82, v83 offset1:1
	ds_write2_b32 v216, v84, v85 offset1:1
	ds_write2_b32 v217, v86, v87 offset1:1
	ds_write2_b32 v218, v88, v89 offset1:1
	ds_write2_b32 v219, v90, v91 offset1:1
	ds_write2_b32 v220, v92, v93 offset1:1
	ds_write2_b32 v221, v94, v95 offset1:1
	ds_write2_b32 v222, v96, v97 offset1:1
	ds_write2_b32 v223, v134, v135 offset1:1
	ds_write2_b32 v224, v136, v137 offset1:1
	ds_write2_b32 v225, v138, v139 offset1:1
	ds_write2_b32 v226, v140, v141 offset1:1
	ds_write2_b32 v227, v142, v143 offset1:1
	ds_write2_b32 v228, v144, v145 offset1:1
	ds_write2_b32 v229, v146, v147 offset1:1
	ds_write2_b32 v230, v148, v149 offset1:1
	s_cbranch_vccnz .LBB0_2181
	s_lshl_b32 s96, s66, 12
	s_and_b32 s96, s96, 0x6000
	s_lshl_b32 s95, s66, 3
	s_and_b32 s95, s95, 8
	s_sub_i32 s94, 0x1ff0, s70
	s_mov_b32 s86, 0xff00ff00
	s_mov_b32 s87, 0xff00ff00
	s_mov_b32 s30, 0x00ff00ff
	s_mov_b32 s31, 0x00ff00ff
	s_mov_b32 s98, 0x1000
	s_mov_b32 s99, 0
	v_and_b32_e32 v40, 15, v166
	v_bfe_u32 v41, v166, 4, 2
	v_lshrrev_b32_e32 v42, 6, v166
	v_lshlrev_b32_e32 v36, 4, v42
	v_and_b32_e32 v37, 63, v166
	v_readfirstlane_b32 s97, v36
	s_lshr_b32 s97, s97, 2
	s_lshl_b32 s59, 12, s97
	s_lshl_b32 s97, 3, s97
	v_lshlrev_b32_e32 v37, 2, v37
	v_add_u32_e32 v37, 0x11200, v37
	ds_read_b32 v133, v37 offset:256
	ds_read_b32 v148, v37 offset:512
	v_mul_u32_u24_e32 v234, 0x90, v40
	v_lshl_add_u32 v234, v41, 4, v234
	v_bfe_u32 v43, v166, 3, 1
	v_lshl_add_u32 v43, v42, 2, v43
	v_add_u32_e32 v236, s94, v43
	v_lshlrev_b32_e32 v44, 2, v41
	v_sub_u32_e32 v239, v236, v44
	v_lshl_add_u32 v45, v42, 5, v40
	v_mul_u32_u24_e32 v45, 0x41, v45
	v_lshl_add_u32 v45, v41, 2, v45
	v_lshlrev_b32_e32 v45, 2, v45
	v_add_u32_e32 v237, 0x9000, v45
	v_add_u32_e32 v238, 0x1040, v237
	v_add_u32_e32 v46, s96, v236
	v_mov_b32_e32 v47, 0
	v_lshlrev_b64 v[46:47], 11, v[46:47]
	v_lshl_add_u64 v[46:47], s[42:43], 0, v[46:47]
	v_and_b32_e32 v48, 7, v166
	v_or_b32_e32 v48, s95, v48
	v_lshlrev_b32_e32 v48, 7, v48
	v_lshl_add_u32 v48, v41, 4, v48
	v_mov_b32_e32 v49, 0
	v_lshl_add_u64 v[46:47], v[46:47], 0, v[48:49]
	global_load_dwordx4 v[66:69], v[46:47], off
	global_load_dwordx4 v[70:73], v[46:47], off offset:64
	v_lshl_add_u64 v[48:49], v[46:47], 0, s[98:99]
	global_load_dwordx4 v[74:77], v[48:49], off
	global_load_dwordx4 v[78:81], v[48:49], off offset:64
	v_mov_b32_e32 v235, 0
	s_lshl_b32 s22, s24, 1
	v_readlane_b32 s20, v231, 14
	s_add_u32 s20, s20, s22
	v_readlane_b32 s21, v231, 10
	s_addc_u32 s21, s21, 0
	s_add_u32 s22, s52, s22
	s_addc_u32 s23, s53, 0
	v_add_u32_e32 v134, v128, v106
	v_add_u32_e32 v135, v128, v108
	v_readfirstlane_b32 s101, v150
	s_mov_b32 s25, 0
	s_waitcnt lgkmcnt(0)
	s_and_b32 s38, s25, 63
	v_readlane_b32 s32, v133, s38
	v_readlane_b32 s38, v148, s38
	s_bitcmp1_b32 s25, 6
	s_cselect_b32 s32, s38, s32
	s_lshl_b32 s32, s32, 13
	s_add_u32 s28, s20, s32
	s_addc_u32 s29, s21, 0
	s_add_u32 s82, s22, s32
	s_addc_u32 s83, s23, 0
	global_load_dwordx4 v[82:85], v134, s[28:29]
	global_load_dwordx4 v[86:89], v134, s[82:83]
	global_load_dwordx4 v[90:93], v135, s[28:29]
	global_load_dwordx4 v[94:97], v135, s[82:83]
	s_cmp_lt_u32 s101, 2
	s_cbranch_scc1 .Lsb16_pa
	s_mov_b32 s58, 1
	s_and_b32 s38, s58, 63
	v_readlane_b32 s32, v133, s38
	v_readlane_b32 s38, v148, s38
	s_bitcmp1_b32 s58, 6
	s_cselect_b32 s32, s38, s32
	s_lshl_b32 s32, s32, 13
	s_add_u32 s28, s20, s32
	s_addc_u32 s29, s21, 0
	s_add_u32 s82, s22, s32
	s_addc_u32 s83, s23, 0
	global_load_dwordx4 v[240:243], v134, s[28:29]
	global_load_dwordx4 v[244:247], v134, s[82:83]
	global_load_dwordx4 v[248:251], v135, s[28:29]
	global_load_dwordx4 v[252:255], v135, s[82:83]
.Lsb16_pa:
	v_and_b32_e32 v36, 0x7f, v133
	v_lshrrev_b32_e32 v37, 5, v36
	v_and_b32_e32 v36, 31, v36
	v_lshlrev_b32_e32 v37, 2, v37
	v_add_u32_e32 v37, 0x11200, v37
	ds_read_b32 v50, v37
	ds_read_b32 v51, v37 offset:16
	ds_read_b32 v52, v37 offset:32
	ds_read_b32 v53, v37 offset:48
	ds_read_b32 v54, v37 offset:64
	ds_read_b32 v55, v37 offset:80
	ds_read_b32 v56, v37 offset:96
	ds_read_b32 v57, v37 offset:112
	ds_read_b32 v58, v37 offset:128
	ds_read_b32 v59, v37 offset:144
	ds_read_b32 v60, v37 offset:160
	ds_read_b32 v61, v37 offset:176
	ds_read_b32 v62, v37 offset:192
	ds_read_b32 v63, v37 offset:208
	ds_read_b32 v64, v37 offset:224
	ds_read_b32 v65, v37 offset:240
	v_mov_b32_e32 v136, 0
	s_waitcnt lgkmcnt(15)
	v_bfe_u32 v38, v50, v36, 1
	v_lshl_or_b32 v136, v38, 0, v136
	s_waitcnt lgkmcnt(14)
	v_bfe_u32 v38, v51, v36, 1
	v_lshl_or_b32 v136, v38, 1, v136
	s_waitcnt lgkmcnt(13)
	v_bfe_u32 v38, v52, v36, 1
	v_lshl_or_b32 v136, v38, 2, v136
	s_waitcnt lgkmcnt(12)
	v_bfe_u32 v38, v53, v36, 1
	v_lshl_or_b32 v136, v38, 3, v136
	s_waitcnt lgkmcnt(11)
	v_bfe_u32 v38, v54, v36, 1
	v_lshl_or_b32 v136, v38, 4, v136
	s_waitcnt lgkmcnt(10)
	v_bfe_u32 v38, v55, v36, 1
	v_lshl_or_b32 v136, v38, 5, v136
	s_waitcnt lgkmcnt(9)
	v_bfe_u32 v38, v56, v36, 1
	v_lshl_or_b32 v136, v38, 6, v136
	s_waitcnt lgkmcnt(8)
	v_bfe_u32 v38, v57, v36, 1
	v_lshl_or_b32 v136, v38, 7, v136
	s_waitcnt lgkmcnt(7)
	v_bfe_u32 v38, v58, v36, 1
	v_lshl_or_b32 v136, v38, 8, v136
	s_waitcnt lgkmcnt(6)
	v_bfe_u32 v38, v59, v36, 1
	v_lshl_or_b32 v136, v38, 9, v136
	s_waitcnt lgkmcnt(5)
	v_bfe_u32 v38, v60, v36, 1
	v_lshl_or_b32 v136, v38, 10, v136
	s_waitcnt lgkmcnt(4)
	v_bfe_u32 v38, v61, v36, 1
	v_lshl_or_b32 v136, v38, 11, v136
	s_waitcnt lgkmcnt(3)
	v_bfe_u32 v38, v62, v36, 1
	v_lshl_or_b32 v136, v38, 12, v136
	s_waitcnt lgkmcnt(2)
	v_bfe_u32 v38, v63, v36, 1
	v_lshl_or_b32 v136, v38, 13, v136
	s_waitcnt lgkmcnt(1)
	v_bfe_u32 v38, v64, v36, 1
	v_lshl_or_b32 v136, v38, 14, v136
	s_waitcnt lgkmcnt(0)
	v_bfe_u32 v38, v65, v36, 1
	v_lshl_or_b32 v136, v38, 15, v136
	s_cmp_lt_u32 s101, 65
	s_cbranch_scc1 .Lsb16_ps
	v_and_b32_e32 v36, 0x7f, v148
	v_lshrrev_b32_e32 v37, 5, v36
	v_and_b32_e32 v36, 31, v36
	v_lshlrev_b32_e32 v37, 2, v37
	v_add_u32_e32 v37, 0x11200, v37
	ds_read_b32 v50, v37
	ds_read_b32 v51, v37 offset:16
	ds_read_b32 v52, v37 offset:32
	ds_read_b32 v53, v37 offset:48
	ds_read_b32 v54, v37 offset:64
	ds_read_b32 v55, v37 offset:80
	ds_read_b32 v56, v37 offset:96
	ds_read_b32 v57, v37 offset:112
	ds_read_b32 v58, v37 offset:128
	ds_read_b32 v59, v37 offset:144
	ds_read_b32 v60, v37 offset:160
	ds_read_b32 v61, v37 offset:176
	ds_read_b32 v62, v37 offset:192
	ds_read_b32 v63, v37 offset:208
	ds_read_b32 v64, v37 offset:224
	ds_read_b32 v65, v37 offset:240
	v_mov_b32_e32 v137, 0
	s_waitcnt lgkmcnt(15)
	v_bfe_u32 v38, v50, v36, 1
	v_lshl_or_b32 v137, v38, 0, v137
	s_waitcnt lgkmcnt(14)
	v_bfe_u32 v38, v51, v36, 1
	v_lshl_or_b32 v137, v38, 1, v137
	s_waitcnt lgkmcnt(13)
	v_bfe_u32 v38, v52, v36, 1
	v_lshl_or_b32 v137, v38, 2, v137
	s_waitcnt lgkmcnt(12)
	v_bfe_u32 v38, v53, v36, 1
	v_lshl_or_b32 v137, v38, 3, v137
	s_waitcnt lgkmcnt(11)
	v_bfe_u32 v38, v54, v36, 1
	v_lshl_or_b32 v137, v38, 4, v137
	s_waitcnt lgkmcnt(10)
	v_bfe_u32 v38, v55, v36, 1
	v_lshl_or_b32 v137, v38, 5, v137
	s_waitcnt lgkmcnt(9)
	v_bfe_u32 v38, v56, v36, 1
	v_lshl_or_b32 v137, v38, 6, v137
	s_waitcnt lgkmcnt(8)
	v_bfe_u32 v38, v57, v36, 1
	v_lshl_or_b32 v137, v38, 7, v137
	s_waitcnt lgkmcnt(7)
	v_bfe_u32 v38, v58, v36, 1
	v_lshl_or_b32 v137, v38, 8, v137
	s_waitcnt lgkmcnt(6)
	v_bfe_u32 v38, v59, v36, 1
	v_lshl_or_b32 v137, v38, 9, v137
	s_waitcnt lgkmcnt(5)
	v_bfe_u32 v38, v60, v36, 1
	v_lshl_or_b32 v137, v38, 10, v137
	s_waitcnt lgkmcnt(4)
	v_bfe_u32 v38, v61, v36, 1
	v_lshl_or_b32 v137, v38, 11, v137
	s_waitcnt lgkmcnt(3)
	v_bfe_u32 v38, v62, v36, 1
	v_lshl_or_b32 v137, v38, 12, v137
	s_waitcnt lgkmcnt(2)
	v_bfe_u32 v38, v63, v36, 1
	v_lshl_or_b32 v137, v38, 13, v137
	s_waitcnt lgkmcnt(1)
	v_bfe_u32 v38, v64, v36, 1
	v_lshl_or_b32 v137, v38, 14, v137
	s_waitcnt lgkmcnt(0)
	v_bfe_u32 v38, v65, v36, 1
	v_lshl_or_b32 v137, v38, 15, v137
.Lsb16_ps:
	s_cmp_lt_u32 s101, 2
	s_cbranch_scc1 .Lsb16_pa2
	s_waitcnt vmcnt(4)
	s_branch .Lsb16_pb

.Lsb16_nost_0:
	s_and_b32 s38, s25, 63
	v_readlane_b32 s32, v136, s38
	v_readlane_b32 s38, v137, s38
	s_bitcmp1_b32 s25, 6
	s_cselect_b32 s77, s38, s32
	s_and_b32 s56, s77, s97
	s_and_b32 s57, s77, s59
	s_or_b32 s28, s56, s57
	s_cmp_eq_u32 s28, 0
	s_cbranch_scc1 .Lsb16_end_0
	s_and_b32 s38, s25, 63
	v_readlane_b32 s32, v133, s38
	v_readlane_b32 s38, v148, s38
	s_bitcmp1_b32 s25, 6
	s_cselect_b32 s76, s38, s32
	s_lshl_b32 s83, s76, 6
	v_subrev_u32_e32 v147, s83, v239
	s_cmp_eq_u32 s56, 0
	s_cbranch_scc1 .Lsb16_g1_0
	ds_read_b128 v[50:53], v234
	ds_read_b128 v[54:57], v234 offset:64
	ds_read_b128 v[58:61], v234 offset:2304
	ds_read_b128 v[62:65], v234 offset:2368
	v_subrev_u32_e32 v146, s94, v236
	v_lshrrev_b32_e64 v146, v146, s77
	v_and_b32_e32 v146, 1, v146
	v_cmp_ne_u32_e32 vcc, 0, v146
	s_nop 1
	v_cndmask_b32_e32 v146, v213, v100, vcc
	s_waitcnt lgkmcnt(3)
	v_mfma_f32_16x16x32_bf16 v[34:37], v[50:53], v[66:69], 0
	s_waitcnt lgkmcnt(2)
	v_mfma_f32_16x16x32_bf16 v[34:37], v[54:57], v[70:73], v[34:37]
	ds_read_b128 v[50:53], v234 offset:4608
	ds_read_b128 v[54:57], v234 offset:4672
	s_waitcnt lgkmcnt(3)
	v_mfma_f32_16x16x32_bf16 v[38:41], v[58:61], v[66:69], 0
	s_waitcnt lgkmcnt(2)
	v_mfma_f32_16x16x32_bf16 v[38:41], v[62:65], v[70:73], v[38:41]
	ds_read_b128 v[58:61], v234 offset:6912
	ds_read_b128 v[62:65], v234 offset:6976
	s_waitcnt lgkmcnt(3)
	v_mfma_f32_16x16x32_bf16 v[42:45], v[50:53], v[66:69], 0
	s_waitcnt lgkmcnt(2)
	v_mfma_f32_16x16x32_bf16 v[42:45], v[54:57], v[70:73], v[42:45]
	s_waitcnt lgkmcnt(1)
	v_mfma_f32_16x16x32_bf16 v[46:49], v[58:61], v[66:69], 0
	s_waitcnt lgkmcnt(0)
	v_mfma_f32_16x16x32_bf16 v[46:49], v[62:65], v[70:73], v[46:49]
	ds_read_b128 v[50:53], v234 offset:9216
	ds_read_b128 v[54:57], v234 offset:9280
	ds_read_b128 v[58:61], v234 offset:11520
	ds_read_b128 v[62:65], v234 offset:11584
	v_fma_f32 v34, v34, s48, v146
	v_fma_f32 v35, v35, s48, v146
	v_fma_f32 v36, v36, s48, v146
	v_fma_f32 v37, v37, s48, v146
	v_fma_f32 v38, v38, s48, v146
	v_fma_f32 v39, v39, s48, v146
	v_fma_f32 v40, v40, s48, v146
	v_fma_f32 v41, v41, s48, v146
	v_fma_f32 v42, v42, s48, v146
	v_fma_f32 v43, v43, s48, v146
	v_fma_f32 v44, v44, s48, v146
	v_fma_f32 v45, v45, s48, v146
	v_fma_f32 v46, v46, s48, v146
	v_fma_f32 v47, v47, s48, v146
	v_fma_f32 v48, v48, s48, v146
	v_fma_f32 v49, v49, s48, v146
	s_cmp_lg_u32 s76, s72
	s_cbranch_scc1 .Lsb16_nm0_0
	v_cmp_le_i32_e64 s[28:29], 0, v147
	s_nop 1
	v_cndmask_b32_e64 v34, v213, v34, s[28:29]
	v_cmp_le_i32_e64 s[28:29], 1, v147
	s_nop 1
	v_cndmask_b32_e64 v35, v213, v35, s[28:29]
	v_cmp_le_i32_e64 s[28:29], 2, v147
	s_nop 1
	v_cndmask_b32_e64 v36, v213, v36, s[28:29]
	v_cmp_le_i32_e64 s[28:29], 3, v147
	s_nop 1
	v_cndmask_b32_e64 v37, v213, v37, s[28:29]
	v_cmp_le_i32_e64 s[28:29], 16, v147
	s_nop 1
	v_cndmask_b32_e64 v38, v213, v38, s[28:29]
	v_cmp_le_i32_e64 s[28:29], 17, v147
	s_nop 1
	v_cndmask_b32_e64 v39, v213, v39, s[28:29]
	v_cmp_le_i32_e64 s[28:29], 18, v147
	s_nop 1
	v_cndmask_b32_e64 v40, v213, v40, s[28:29]
	v_cmp_le_i32_e64 s[28:29], 19, v147
	s_nop 1
	v_cndmask_b32_e64 v41, v213, v41, s[28:29]
	v_cmp_le_i32_e64 s[28:29], 32, v147
	s_nop 1
	v_cndmask_b32_e64 v42, v213, v42, s[28:29]
	v_cmp_le_i32_e64 s[28:29], 33, v147
	s_nop 1
	v_cndmask_b32_e64 v43, v213, v43, s[28:29]
	v_cmp_le_i32_e64 s[28:29], 34, v147
	s_nop 1
	v_cndmask_b32_e64 v44, v213, v44, s[28:29]
	v_cmp_le_i32_e64 s[28:29], 35, v147
	s_nop 1
	v_cndmask_b32_e64 v45, v213, v45, s[28:29]
	v_cmp_le_i32_e64 s[28:29], 48, v147
	s_nop 1
	v_cndmask_b32_e64 v46, v213, v46, s[28:29]
	v_cmp_le_i32_e64 s[28:29], 49, v147
	s_nop 1
	v_cndmask_b32_e64 v47, v213, v47, s[28:29]
	v_cmp_le_i32_e64 s[28:29], 50, v147
	s_nop 1
	v_cndmask_b32_e64 v48, v213, v48, s[28:29]
	v_cmp_le_i32_e64 s[28:29], 51, v147
	s_nop 1
	v_cndmask_b32_e64 v49, v213, v49, s[28:29]

.Lsb16_g1_0:
	s_cmp_eq_u32 s57, 0
	s_cbranch_scc1 .Lsb16_end_0
	ds_read_b128 v[50:53], v234
	ds_read_b128 v[54:57], v234 offset:64
	ds_read_b128 v[58:61], v234 offset:2304
	ds_read_b128 v[62:65], v234 offset:2368
	v_add_u32_e32 v147, 2, v147
	v_subrev_u32_e32 v146, s94, v236
	v_add_u32_e32 v146, 2, v146
	v_lshrrev_b32_e64 v146, v146, s77
	v_and_b32_e32 v146, 1, v146
	v_cmp_ne_u32_e32 vcc, 0, v146
	s_nop 1
	v_cndmask_b32_e32 v146, v213, v100, vcc
	s_waitcnt lgkmcnt(3)
	v_mfma_f32_16x16x32_bf16 v[34:37], v[50:53], v[74:77], 0
	s_waitcnt lgkmcnt(2)
	v_mfma_f32_16x16x32_bf16 v[34:37], v[54:57], v[78:81], v[34:37]
	ds_read_b128 v[50:53], v234 offset:4608
	ds_read_b128 v[54:57], v234 offset:4672
	s_waitcnt lgkmcnt(3)
	v_mfma_f32_16x16x32_bf16 v[38:41], v[58:61], v[74:77], 0
	s_waitcnt lgkmcnt(2)
	v_mfma_f32_16x16x32_bf16 v[38:41], v[62:65], v[78:81], v[38:41]
	ds_read_b128 v[58:61], v234 offset:6912
	ds_read_b128 v[62:65], v234 offset:6976
	s_waitcnt lgkmcnt(3)
	v_mfma_f32_16x16x32_bf16 v[42:45], v[50:53], v[74:77], 0
	s_waitcnt lgkmcnt(2)
	v_mfma_f32_16x16x32_bf16 v[42:45], v[54:57], v[78:81], v[42:45]
	s_waitcnt lgkmcnt(1)
	v_mfma_f32_16x16x32_bf16 v[46:49], v[58:61], v[74:77], 0
	s_waitcnt lgkmcnt(0)
	v_mfma_f32_16x16x32_bf16 v[46:49], v[62:65], v[78:81], v[46:49]
	ds_read_b128 v[50:53], v234 offset:9216
	ds_read_b128 v[54:57], v234 offset:9280
	ds_read_b128 v[58:61], v234 offset:11520
	ds_read_b128 v[62:65], v234 offset:11584
	v_fma_f32 v34, v34, s48, v146
	v_fma_f32 v35, v35, s48, v146
	v_fma_f32 v36, v36, s48, v146
	v_fma_f32 v37, v37, s48, v146
	v_fma_f32 v38, v38, s48, v146
	v_fma_f32 v39, v39, s48, v146
	v_fma_f32 v40, v40, s48, v146
	v_fma_f32 v41, v41, s48, v146
	v_fma_f32 v42, v42, s48, v146
	v_fma_f32 v43, v43, s48, v146
	v_fma_f32 v44, v44, s48, v146
	v_fma_f32 v45, v45, s48, v146
	v_fma_f32 v46, v46, s48, v146
	v_fma_f32 v47, v47, s48, v146
	v_fma_f32 v48, v48, s48, v146
	v_fma_f32 v49, v49, s48, v146
	s_cmp_lg_u32 s76, s72
	s_cbranch_scc1 .Lsb16_nm1_0
	v_cmp_le_i32_e64 s[28:29], 0, v147
	s_nop 1
	v_cndmask_b32_e64 v34, v213, v34, s[28:29]
	v_cmp_le_i32_e64 s[28:29], 1, v147
	s_nop 1
	v_cndmask_b32_e64 v35, v213, v35, s[28:29]
	v_cmp_le_i32_e64 s[28:29], 2, v147
	s_nop 1
	v_cndmask_b32_e64 v36, v213, v36, s[28:29]
	v_cmp_le_i32_e64 s[28:29], 3, v147
	s_nop 1
	v_cndmask_b32_e64 v37, v213, v37, s[28:29]
	v_cmp_le_i32_e64 s[28:29], 16, v147
	s_nop 1
	v_cndmask_b32_e64 v38, v213, v38, s[28:29]
	v_cmp_le_i32_e64 s[28:29], 17, v147
	s_nop 1
	v_cndmask_b32_e64 v39, v213, v39, s[28:29]
	v_cmp_le_i32_e64 s[28:29], 18, v147
	s_nop 1
	v_cndmask_b32_e64 v40, v213, v40, s[28:29]
	v_cmp_le_i32_e64 s[28:29], 19, v147
	s_nop 1
	v_cndmask_b32_e64 v41, v213, v41, s[28:29]
	v_cmp_le_i32_e64 s[28:29], 32, v147
	s_nop 1
	v_cndmask_b32_e64 v42, v213, v42, s[28:29]
	v_cmp_le_i32_e64 s[28:29], 33, v147
	s_nop 1
	v_cndmask_b32_e64 v43, v213, v43, s[28:29]
	v_cmp_le_i32_e64 s[28:29], 34, v147
	s_nop 1
	v_cndmask_b32_e64 v44, v213, v44, s[28:29]
	v_cmp_le_i32_e64 s[28:29], 35, v147
	s_nop 1
	v_cndmask_b32_e64 v45, v213, v45, s[28:29]
	v_cmp_le_i32_e64 s[28:29], 48, v147
	s_nop 1
	v_cndmask_b32_e64 v46, v213, v46, s[28:29]
	v_cmp_le_i32_e64 s[28:29], 49, v147
	s_nop 1
	v_cndmask_b32_e64 v47, v213, v47, s[28:29]
	v_cmp_le_i32_e64 s[28:29], 50, v147
	s_nop 1
	v_cndmask_b32_e64 v48, v213, v48, s[28:29]
	v_cmp_le_i32_e64 s[28:29], 51, v147
	s_nop 1
	v_cndmask_b32_e64 v49, v213, v49, s[28:29]

.Lsb16_nost_1:
	s_and_b32 s38, s25, 63
	v_readlane_b32 s32, v136, s38
	v_readlane_b32 s38, v137, s38
	s_bitcmp1_b32 s25, 6
	s_cselect_b32 s77, s38, s32
	s_and_b32 s56, s77, s97
	s_and_b32 s57, s77, s59
	s_or_b32 s28, s56, s57
	s_cmp_eq_u32 s28, 0
	s_cbranch_scc1 .Lsb16_end_1
	s_and_b32 s38, s25, 63
	v_readlane_b32 s32, v133, s38
	v_readlane_b32 s38, v148, s38
	s_bitcmp1_b32 s25, 6
	s_cselect_b32 s76, s38, s32
	s_lshl_b32 s83, s76, 6
	v_subrev_u32_e32 v147, s83, v239
	s_cmp_eq_u32 s56, 0
	s_cbranch_scc1 .Lsb16_g1_1
	ds_read_b128 v[50:53], v234 offset:18432
	ds_read_b128 v[54:57], v234 offset:18496
	ds_read_b128 v[58:61], v234 offset:20736
	ds_read_b128 v[62:65], v234 offset:20800
	v_subrev_u32_e32 v146, s94, v236
	v_lshrrev_b32_e64 v146, v146, s77
	v_and_b32_e32 v146, 1, v146
	v_cmp_ne_u32_e32 vcc, 0, v146
	s_nop 1
	v_cndmask_b32_e32 v146, v213, v100, vcc
	s_waitcnt lgkmcnt(3)
	v_mfma_f32_16x16x32_bf16 v[34:37], v[50:53], v[66:69], 0
	s_waitcnt lgkmcnt(2)
	v_mfma_f32_16x16x32_bf16 v[34:37], v[54:57], v[70:73], v[34:37]
	ds_read_b128 v[50:53], v234 offset:23040
	ds_read_b128 v[54:57], v234 offset:23104
	s_waitcnt lgkmcnt(3)
	v_mfma_f32_16x16x32_bf16 v[38:41], v[58:61], v[66:69], 0
	s_waitcnt lgkmcnt(2)
	v_mfma_f32_16x16x32_bf16 v[38:41], v[62:65], v[70:73], v[38:41]
	ds_read_b128 v[58:61], v234 offset:25344
	ds_read_b128 v[62:65], v234 offset:25408
	s_waitcnt lgkmcnt(3)
	v_mfma_f32_16x16x32_bf16 v[42:45], v[50:53], v[66:69], 0
	s_waitcnt lgkmcnt(2)
	v_mfma_f32_16x16x32_bf16 v[42:45], v[54:57], v[70:73], v[42:45]
	s_waitcnt lgkmcnt(1)
	v_mfma_f32_16x16x32_bf16 v[46:49], v[58:61], v[66:69], 0
	s_waitcnt lgkmcnt(0)
	v_mfma_f32_16x16x32_bf16 v[46:49], v[62:65], v[70:73], v[46:49]
	ds_read_b128 v[50:53], v234 offset:27648
	ds_read_b128 v[54:57], v234 offset:27712
	ds_read_b128 v[58:61], v234 offset:29952
	ds_read_b128 v[62:65], v234 offset:30016
	v_fma_f32 v34, v34, s48, v146
	v_fma_f32 v35, v35, s48, v146
	v_fma_f32 v36, v36, s48, v146
	v_fma_f32 v37, v37, s48, v146
	v_fma_f32 v38, v38, s48, v146
	v_fma_f32 v39, v39, s48, v146
	v_fma_f32 v40, v40, s48, v146
	v_fma_f32 v41, v41, s48, v146
	v_fma_f32 v42, v42, s48, v146
	v_fma_f32 v43, v43, s48, v146
	v_fma_f32 v44, v44, s48, v146
	v_fma_f32 v45, v45, s48, v146
	v_fma_f32 v46, v46, s48, v146
	v_fma_f32 v47, v47, s48, v146
	v_fma_f32 v48, v48, s48, v146
	v_fma_f32 v49, v49, s48, v146
	s_cmp_lg_u32 s76, s72
	s_cbranch_scc1 .Lsb16_nm0_1
	v_cmp_le_i32_e64 s[28:29], 0, v147
	s_nop 1
	v_cndmask_b32_e64 v34, v213, v34, s[28:29]
	v_cmp_le_i32_e64 s[28:29], 1, v147
	s_nop 1
	v_cndmask_b32_e64 v35, v213, v35, s[28:29]
	v_cmp_le_i32_e64 s[28:29], 2, v147
	s_nop 1
	v_cndmask_b32_e64 v36, v213, v36, s[28:29]
	v_cmp_le_i32_e64 s[28:29], 3, v147
	s_nop 1
	v_cndmask_b32_e64 v37, v213, v37, s[28:29]
	v_cmp_le_i32_e64 s[28:29], 16, v147
	s_nop 1
	v_cndmask_b32_e64 v38, v213, v38, s[28:29]
	v_cmp_le_i32_e64 s[28:29], 17, v147
	s_nop 1
	v_cndmask_b32_e64 v39, v213, v39, s[28:29]
	v_cmp_le_i32_e64 s[28:29], 18, v147
	s_nop 1
	v_cndmask_b32_e64 v40, v213, v40, s[28:29]
	v_cmp_le_i32_e64 s[28:29], 19, v147
	s_nop 1
	v_cndmask_b32_e64 v41, v213, v41, s[28:29]
	v_cmp_le_i32_e64 s[28:29], 32, v147
	s_nop 1
	v_cndmask_b32_e64 v42, v213, v42, s[28:29]
	v_cmp_le_i32_e64 s[28:29], 33, v147
	s_nop 1
	v_cndmask_b32_e64 v43, v213, v43, s[28:29]
	v_cmp_le_i32_e64 s[28:29], 34, v147
	s_nop 1
	v_cndmask_b32_e64 v44, v213, v44, s[28:29]
	v_cmp_le_i32_e64 s[28:29], 35, v147
	s_nop 1
	v_cndmask_b32_e64 v45, v213, v45, s[28:29]
	v_cmp_le_i32_e64 s[28:29], 48, v147
	s_nop 1
	v_cndmask_b32_e64 v46, v213, v46, s[28:29]
	v_cmp_le_i32_e64 s[28:29], 49, v147
	s_nop 1
	v_cndmask_b32_e64 v47, v213, v47, s[28:29]
	v_cmp_le_i32_e64 s[28:29], 50, v147
	s_nop 1
	v_cndmask_b32_e64 v48, v213, v48, s[28:29]
	v_cmp_le_i32_e64 s[28:29], 51, v147
	s_nop 1
	v_cndmask_b32_e64 v49, v213, v49, s[28:29]

.Lsb16_g1_1:
	s_cmp_eq_u32 s57, 0
	s_cbranch_scc1 .Lsb16_end_1
	ds_read_b128 v[50:53], v234 offset:18432
	ds_read_b128 v[54:57], v234 offset:18496
	ds_read_b128 v[58:61], v234 offset:20736
	ds_read_b128 v[62:65], v234 offset:20800
	v_add_u32_e32 v147, 2, v147
	v_subrev_u32_e32 v146, s94, v236
	v_add_u32_e32 v146, 2, v146
	v_lshrrev_b32_e64 v146, v146, s77
	v_and_b32_e32 v146, 1, v146
	v_cmp_ne_u32_e32 vcc, 0, v146
	s_nop 1
	v_cndmask_b32_e32 v146, v213, v100, vcc
	s_waitcnt lgkmcnt(3)
	v_mfma_f32_16x16x32_bf16 v[34:37], v[50:53], v[74:77], 0
	s_waitcnt lgkmcnt(2)
	v_mfma_f32_16x16x32_bf16 v[34:37], v[54:57], v[78:81], v[34:37]
	ds_read_b128 v[50:53], v234 offset:23040
	ds_read_b128 v[54:57], v234 offset:23104
	s_waitcnt lgkmcnt(3)
	v_mfma_f32_16x16x32_bf16 v[38:41], v[58:61], v[74:77], 0
	s_waitcnt lgkmcnt(2)
	v_mfma_f32_16x16x32_bf16 v[38:41], v[62:65], v[78:81], v[38:41]
	ds_read_b128 v[58:61], v234 offset:25344
	ds_read_b128 v[62:65], v234 offset:25408
	s_waitcnt lgkmcnt(3)
	v_mfma_f32_16x16x32_bf16 v[42:45], v[50:53], v[74:77], 0
	s_waitcnt lgkmcnt(2)
	v_mfma_f32_16x16x32_bf16 v[42:45], v[54:57], v[78:81], v[42:45]
	s_waitcnt lgkmcnt(1)
	v_mfma_f32_16x16x32_bf16 v[46:49], v[58:61], v[74:77], 0
	s_waitcnt lgkmcnt(0)
	v_mfma_f32_16x16x32_bf16 v[46:49], v[62:65], v[78:81], v[46:49]
	ds_read_b128 v[50:53], v234 offset:27648
	ds_read_b128 v[54:57], v234 offset:27712
	ds_read_b128 v[58:61], v234 offset:29952
	ds_read_b128 v[62:65], v234 offset:30016
	v_fma_f32 v34, v34, s48, v146
	v_fma_f32 v35, v35, s48, v146
	v_fma_f32 v36, v36, s48, v146
	v_fma_f32 v37, v37, s48, v146
	v_fma_f32 v38, v38, s48, v146
	v_fma_f32 v39, v39, s48, v146
	v_fma_f32 v40, v40, s48, v146
	v_fma_f32 v41, v41, s48, v146
	v_fma_f32 v42, v42, s48, v146
	v_fma_f32 v43, v43, s48, v146
	v_fma_f32 v44, v44, s48, v146
	v_fma_f32 v45, v45, s48, v146
	v_fma_f32 v46, v46, s48, v146
	v_fma_f32 v47, v47, s48, v146
	v_fma_f32 v48, v48, s48, v146
	v_fma_f32 v49, v49, s48, v146
	s_cmp_lg_u32 s76, s72
	s_cbranch_scc1 .Lsb16_nm1_1
	v_cmp_le_i32_e64 s[28:29], 0, v147
	s_nop 1
	v_cndmask_b32_e64 v34, v213, v34, s[28:29]
	v_cmp_le_i32_e64 s[28:29], 1, v147
	s_nop 1
	v_cndmask_b32_e64 v35, v213, v35, s[28:29]
	v_cmp_le_i32_e64 s[28:29], 2, v147
	s_nop 1
	v_cndmask_b32_e64 v36, v213, v36, s[28:29]
	v_cmp_le_i32_e64 s[28:29], 3, v147
	s_nop 1
	v_cndmask_b32_e64 v37, v213, v37, s[28:29]
	v_cmp_le_i32_e64 s[28:29], 16, v147
	s_nop 1
	v_cndmask_b32_e64 v38, v213, v38, s[28:29]
	v_cmp_le_i32_e64 s[28:29], 17, v147
	s_nop 1
	v_cndmask_b32_e64 v39, v213, v39, s[28:29]
	v_cmp_le_i32_e64 s[28:29], 18, v147
	s_nop 1
	v_cndmask_b32_e64 v40, v213, v40, s[28:29]
	v_cmp_le_i32_e64 s[28:29], 19, v147
	s_nop 1
	v_cndmask_b32_e64 v41, v213, v41, s[28:29]
	v_cmp_le_i32_e64 s[28:29], 32, v147
	s_nop 1
	v_cndmask_b32_e64 v42, v213, v42, s[28:29]
	v_cmp_le_i32_e64 s[28:29], 33, v147
	s_nop 1
	v_cndmask_b32_e64 v43, v213, v43, s[28:29]
	v_cmp_le_i32_e64 s[28:29], 34, v147
	s_nop 1
	v_cndmask_b32_e64 v44, v213, v44, s[28:29]
	v_cmp_le_i32_e64 s[28:29], 35, v147
	s_nop 1
	v_cndmask_b32_e64 v45, v213, v45, s[28:29]
	v_cmp_le_i32_e64 s[28:29], 48, v147
	s_nop 1
	v_cndmask_b32_e64 v46, v213, v46, s[28:29]
	v_cmp_le_i32_e64 s[28:29], 49, v147
	s_nop 1
	v_cndmask_b32_e64 v47, v213, v47, s[28:29]
	v_cmp_le_i32_e64 s[28:29], 50, v147
	s_nop 1
	v_cndmask_b32_e64 v48, v213, v48, s[28:29]
	v_cmp_le_i32_e64 s[28:29], 51, v147
	s_nop 1
	v_cndmask_b32_e64 v49, v213, v49, s[28:29]
